# weight conversion split three ways: 3072 items at the end of P8, 1664 at the end of P6 (workgroups 128-255), 4480 in P5 (three rounds)
# baseline (speedup 1.0000x reference)
.LBB0_790:
	s_cmpk_lg_i32 s34, 0x100
	s_cbranch_scc1 .Lcv5_orig
	v_readlane_b32 s0, v255, 43
	s_cmp_eq_u32 s0, 3
	s_cbranch_scc1 .LBB0_881
	v_readlane_b32 s0, v254, 34
	s_movk_i32 s1, 0x5e0
	s_movk_i32 s101, 9216
	s_cmp_lt_i32 s0, 0
	s_cbranch_scc1 .Lcv5_gemm
	s_addk_i32 s0, 4736
	s_branch .Lcv5_go
.Lcv5_gemm:
	s_addk_i32 s0, 0x220
	s_cmpk_ge_i32 s0, 0
	s_cbranch_scc1 .LBB0_881
	s_addk_i32 s0, 9216
	s_movk_i32 s1, 0x220
	s_movk_i32 s101, 0x2400

.LBB0_880:
	v_readlane_b32 s52, v255, 40
	v_readlane_b32 s53, v255, 41
	v_readlane_b32 s96, v254, 29
	v_readlane_b32 s20, v255, 39
	v_readlane_b32 s26, v255, 21
	s_mov_b64 s[42:43], 0x60
	v_readlane_b32 s33, v255, 42
	s_cmp_eq_u32 s100, 8
	s_cbranch_scc1 .Lcv_ret8
	s_cmp_eq_u32 s100, 6
	s_cbranch_scc1 .Lcv_ret6

.LBB0_986:
	s_cmpk_lg_i32 s34, 0x100
	s_cbranch_scc1 .Lcv_skip6
	v_readlane_b32 s0, v255, 43
	s_cmp_eq_u32 s0, 3
	s_cbranch_scc1 .Lcv_skip6
	s_cmpk_lt_u32 s2, 128
	s_cbranch_scc1 .Lcv_skip6
	v_readlane_b32 s0, v254, 34
	s_movk_i32 s1, 0x400
	s_movk_i32 s101, 4736
	s_addk_i32 s0, 2592
	v_writelane_b32 v255, s1, 57
	s_nop 1
	v_writelane_b32 v255, s0, 58
	s_nop 1
	s_mov_b32 s100, 6
	s_branch .Lcv_entry
.Lcv_ret6:
	s_mov_b32 s100, 0
.Lcv_skip6:
	s_waitcnt vmcnt(0)
	s_barrier
	s_mov_b64 s[0:1], exec
	v_readlane_b32 s4, v253, 32
	v_readlane_b32 s5, v253, 33
	s_and_b64 s[4:5], s[0:1], s[4:5]
	s_mov_b64 exec, s[4:5]
	s_cbranch_execz .LBB0_1037
	v_readlane_b32 s4, v255, 36
	s_getreg_b32 s3, hwreg(HW_REG_XCC_ID, 0, 4)
	s_waitcnt vmcnt(0) expcnt(0) lgkmcnt(0)
	v_mov_b32_e32 v0, s4
	ds_read_b32 v2, v0
	v_readlane_b32 s4, v255, 37
	s_waitcnt lgkmcnt(0)
	v_cmp_ne_u32_e32 vcc, 0, v2
	v_mov_b32_e32 v0, s4
	ds_read_b32 v0, v0
	s_cbranch_vccnz .LBB0_1001
	s_and_b32 s4, s3, 15
	s_lshl_b32 s7, s4, 8
	s_mov_b32 s10, 0
	s_branch .LBB0_990
